# up-projection GEMM also uses the whole-line LDS-DMA image
# baseline (speedup 1.0000x reference)
; template <class Epi, class Sched, bool ALIGN_EPI = false, bool SP2 = false>
; __device__ __forceinline__ void gemm_phase(PG8_LAS unsigned char* lds, const Gemm g, const Sched& S, const Epi& E) {
;     ...
;     for (int i = 0; i < 2; ++i) { int R, C; stage_rc(tid * 16 + i * 8192, R, C); const int Rb = Epi::PERM ? ((R & ~31) + perm32(R & 31)) : R;
;         voffA[i] = (unsigned)(R * K + C) * 2u; voffB[i] = (unsigned)(Rb * K + C) * 2u; }
; __global__ void __launch_bounds__(NTHREADS, 2) fwd_kernel(Params p) {
;     ...
;     if (RUN(9)) {
;         pg8::Gemm g{(const bf16_t*)(ws + WS_X1B), (const bf16_t*)(ws + WS_WUP), T, NUP, DM}; pg8::StaticOrder S; S.init(T, NUP, G, cid);
;         EpiGlu E{(bf16_t*)(ws + WS_ACT), (bf16_t*)(ws + WS_EDGE), p.in[14], p.in[15]};
;         pg8::gemm_phase<EpiGlu, pg8::StaticOrder, true, true>(ring, g, S, E);
.LBB0_870:
	v_readlane_b32 s4, v246, 12
	s_cmp_lt_i32 s4, 10
	s_cselect_b64 s[22:23], -1, 0
	s_and_b64 s[0:1], s[22:23], s[0:1]
	s_andn2_b64 vcc, exec, s[0:1]
	v_readlane_b32 s5, v246, 13
	v_readlane_b32 s6, v246, 14
	v_readlane_b32 s7, v246, 15
	s_cbranch_vccnz .LBB0_917
	v_lshrrev_b32_e32 v238, 3, v144
	v_and_b32_e32 v239, 7, v144
	v_and_b32_e32 v240, 7, v238
	v_xor_b32_e32 v239, v239, v240
	v_lshlrev_b32_e32 v239, 4, v239
	v_lshl_or_b32 v240, v238, 12, v239
	v_add_u32_e32 v241, 0x40000, v240
	v_and_b32_e32 v242, 31, v238
	v_bfe_u32 v243, v242, 2, 2
	v_lshlrev_b32_e32 v243, 3, v243
	v_lshrrev_b32_e32 v230, 4, v242
	v_lshl_or_b32 v243, v230, 2, v243
	v_and_b32_e32 v230, 3, v242
	v_or_b32_e32 v243, v243, v230
	v_and_b32_e32 v230, 32, v238
	v_or_b32_e32 v243, v243, v230
	v_lshl_or_b32 v238, v243, 12, v239
	v_add_u32_e32 v239, 0x40000, v238
	v_readlane_b32 s0, v246, 0
	v_readlane_b32 s1, v246, 1
	s_mov_b32 s2, s0
	s_cmpk_lt_i32 s0, 0x1580
	s_cselect_b64 s[0:1], -1, 0
	s_cmpk_gt_i32 s2, 0x157f
	v_readfirstlane_b32 s2, v144
	s_cbranch_scc1 .LBB0_873
	v_readlane_b32 s4, v246, 0
	s_ashr_i32 s3, s4, 31
	s_lshr_b32 s3, s3, 29
	s_add_i32 s3, s4, s3
	s_mov_b32 s6, s4
	s_ashr_i32 s4, s3, 3
	s_and_b32 s3, s3, -8
	v_readlane_b32 s5, v246, 1
	s_sub_i32 s3, s6, s3
	s_cmp_lt_i32 s3, 0
	s_movk_i32 s5, 0x2b1
	s_cselect_b32 s5, s5, 0x2b0
	s_mul_i32 s3, s3, s5
	s_add_i32 s3, s3, s4
	s_mul_hi_i32 s4, s3, 0x2fa0be83
	s_lshr_b32 s5, s4, 31
	s_ashr_i32 s4, s4, 6
	s_add_i32 s4, s4, s5
	s_lshl_b32 s5, s4, 3
	s_mulk_i32 s4, 0x158
	s_sub_i32 s3, s3, s4
	s_sext_i32_i16 s4, s3
	s_bfe_u32 s4, s4, 0x3001c
	s_add_i32 s4, s3, s4
	s_sext_i32_i16 s6, s4
	s_and_b32 s4, s4, 0xfff8
	s_sub_i32 s3, s3, s4
	s_sext_i32_i16 s3, s3
	s_add_i32 s14, s5, s3
	s_ashr_i32 s16, s6, 3
.LBB0_873:
	s_andn2_b64 vcc, exec, s[0:1]
	s_cbranch_vccnz .LBB0_917
	v_readlane_b32 s0, v246, 10
	v_readlane_b32 s1, v246, 11
	s_add_u32 s33, s0, 0x8800000
	s_waitcnt lgkmcnt(0)
	v_lshrrev_b32_e32 v2, 1, v144
	v_lshrrev_b32_e32 v3, 5, v144
	s_addc_u32 s35, s1, 0
	v_and_b32_e32 v2, 24, v2
	v_and_b32_e32 v3, 4, v3
	v_bfe_u32 v4, v144, 2, 2
	s_add_u32 s56, s0, 0x3e00000
	v_lshlrev_b32_e32 v0, 4, v144
	v_and_b32_e32 v1, 32, v144
	s_waitcnt vmcnt(0)
	v_bfe_u32 v10, v144, 2, 4
	v_or3_b32 v2, v3, v4, v2
	v_lshrrev_b32_e32 v3, 3, v144
	s_movk_i32 s0, 0x70
	v_bitop3_b32 v8, v0, v1, 48 bitop3:0x6c
	v_and_b32_e32 v9, 64, v144
	v_and_or_b32 v4, v3, s0, v10
	s_movk_i32 s0, 0x60
	v_add_u32_e32 v11, 0x2000, v0
	v_or_b32_e32 v1, v8, v9
	v_and_or_b32 v3, v3, s0, v2
	v_lshrrev_b32_e32 v0, 7, v11
	s_movk_i32 s0, 0xf0
	v_lshl_or_b32 v148, v3, 12, v1
	v_mov_b32_e32 v148, v238
	v_and_or_b32 v3, v0, s0, v10
	s_movk_i32 s0, 0xe0
	s_addc_u32 s57, s1, 0
	v_and_or_b32 v0, v0, s0, v2
	s_lshr_b32 s0, s2, 6
	s_ashr_i32 s15, s14, 31
	s_ashr_i32 s17, s16, 31
	s_lshr_b32 s58, s2, 8
	s_lshl_b32 s59, s0, 10
	s_lshl_b64 s[4:5], s[14:15], 20
	s_lshl_b64 s[6:7], s[16:17], 20
	s_add_u32 s20, s56, s6
	s_addc_u32 s21, s57, s7
	s_add_i32 s60, s59, 0
	s_add_i32 m0, s60, 0x10000
	v_lshl_or_b32 v152, v0, 12, v1
	v_mov_b32_e32 v152, v239
	global_load_lds_dwordx4 v148, s[20:21]
	s_add_i32 m0, s60, 0x12000
	s_add_u32 s6, s20, 0x80000
	global_load_lds_dwordx4 v152, s[20:21]
	s_addc_u32 s7, s21, 0
	s_add_i32 m0, s60, 0x14000
	v_lshl_or_b32 v146, v4, 12, v1
	v_mov_b32_e32 v146, v240
	global_load_lds_dwordx4 v148, s[6:7]
	s_add_i32 m0, s60, 0x16000
	s_add_u32 s18, s33, s4
	s_addc_u32 s19, s35, s5
	s_add_i32 s61, s60, 0x2000
	global_load_lds_dwordx4 v152, s[6:7]
	s_mov_b32 m0, s60
	s_add_u32 s4, s18, 0x80000
	v_lshl_or_b32 v150, v3, 12, v1
	v_mov_b32_e32 v150, v241
	global_load_lds_dwordx4 v146, s[18:19]
	s_mov_b32 m0, s61
	s_addc_u32 s5, s19, 0
	s_add_i32 s62, s60, 0x4000
	global_load_lds_dwordx4 v150, s[18:19]
	s_mov_b32 m0, s62
	s_add_i32 s63, s60, 0x6000
	global_load_lds_dwordx4 v146, s[4:5]
	s_mov_b32 m0, s63
	v_mov_b32_e32 v155, 0
	global_load_lds_dwordx4 v150, s[4:5]
	v_mov_b32_e32 v149, v155
	v_mov_b32_e32 v153, v155
	v_mov_b32_e32 v147, v155
	v_mov_b32_e32 v151, v155
	s_cmp_eq_u32 s58, 1
	s_mov_b32 s64, 0
	v_lshl_add_u64 v[6:7], s[20:21], 0, v[148:149]
	v_lshl_add_u64 v[4:5], s[20:21], 0, v[152:153]
	v_lshl_add_u64 v[0:1], s[18:19], 0, v[146:147]
	s_cselect_b64 s[24:25], -1, 0
	s_cmp_lg_u32 s58, 1
	v_lshl_add_u64 v[2:3], s[18:19], 0, v[150:151]
	s_cbranch_scc1 .LBB0_876
	s_barrier
; #define PG8_STAGE(bufoff, gbase, voff) do { _Pragma("unroll") for (int _i = 0; _i < 2; ++_i) \
;         __builtin_amdgcn_global_load_lds((const unsigned*)((const char*)(gbase) + (voff)[_i]), (PG8_LAS unsigned*)(lds + (bufoff) + ldsw + _i * 8192), 16, 0, 0); } while (0)
; #define PG8_WAIT_V(n) asm volatile("s_waitcnt vmcnt(" #n ")" ::: "memory")
; #define PG8_BAR __builtin_amdgcn_s_barrier()
; template <class Epi, class Sched, bool ALIGN_EPI = false, bool SP2 = false>
; __device__ __forceinline__ void gemm_phase(PG8_LAS unsigned char* lds, const Gemm g, const Sched& S, const Epi& E) {
;     ...
;         PG8_STAGE(PG8_SB(0, 0), cB, voffB); PG8_STAGE(PG8_SB(0, 1), cB + hstep, voffB); PG8_STAGE(PG8_SA(0, 0), cA, voffA); PG8_STAGE(PG8_SA(0, 1), cA + hstep, voffA);
;         if (wr == 1) PG8_BAR;
;         PG8_WAIT_V(2); PG8_BAR;
;         PG8_STAGE(PG8_SB(1, 0), cB + kstep, voffB); PG8_STAGE(PG8_SA(1, 0), cA + kstep, voffA); PG8_STAGE(PG8_SB(1, 1), cB + hstep + kstep, voffB);
;         PG8_WAIT_V(6); PG8_BAR;
;     __device__ __forceinline__ void operator()(const f32x4 (&acc)[2][2][4][2], const pg8::Unit& u, int wr, int wc, int fr, int fq) const {
;         const int j0 = u.pn * 128 + wc * 32 + 8 * fq;
;         const int lane = fq * 16 + fr, psrc = (lane & 48) | ((fr + 15) & 15), nsrc = (lane & 48) | ((fr + 1) & 15);
.LBB0_876:
	v_readlane_b32 s4, v246, 10
	v_readlane_b32 s5, v246, 11
	s_add_u32 s26, s4, 0x26000000
	s_addc_u32 s27, s5, 0
	s_add_u32 s65, s4, 0x10800000
	s_addc_u32 s66, s5, 0
	s_lshl_b32 s0, s0, 5
	s_mov_b64 s[28:29], 0x80
	s_and_b32 s12, s0, 0x60
	s_add_i32 m0, s60, 0x18000
	v_lshl_add_u64 v[6:7], v[6:7], 0, s[28:29]
	s_lshl_b32 s3, s58, 13
	s_lshl_b32 s4, s12, 7
	s_waitcnt vmcnt(2)
	s_barrier
	global_load_lds_dwordx4 v[6:7], off
	v_lshl_add_u64 v[4:5], v[4:5], 0, s[28:29]
	s_add_i32 m0, s60, 0x1a000
	s_add_i32 s67, s60, 0x8000
	s_add_i32 s68, s60, 0xa000
	global_load_lds_dwordx4 v[4:5], off
	v_lshl_add_u64 v[0:1], v[0:1], 0, s[28:29]
	s_mov_b32 m0, s67
	s_add_u32 s0, s20, 0x80080
	global_load_lds_dwordx4 v[0:1], off
	v_lshl_add_u64 v[0:1], v[2:3], 0, s[28:29]
	s_mov_b32 m0, s68
	s_addc_u32 s1, s21, 0
	global_load_lds_dwordx4 v[0:1], off
	s_add_i32 m0, s60, 0x1c000
	v_lshl_add_u64 v[0:1], s[0:1], 0, v[148:149]
	global_load_lds_dwordx4 v[0:1], off
	v_lshl_add_u64 v[0:1], s[0:1], 0, v[152:153]
	s_add_i32 m0, s60, 0x1e000
	v_and_b32_e32 v145, 15, v144
	global_load_lds_dwordx4 v[0:1], off
	v_bfe_u32 v0, v144, 4, 2
	v_lshlrev_b32_e32 v1, 4, v0
	v_lshlrev_b32_e32 v3, 2, v144
	v_lshlrev_b32_e32 v4, 6, v144
	s_movk_i32 s0, 0x3c0
	v_lshl_or_b32 v2, v145, 6, v1
	v_and_b32_e32 v3, 32, v3
	v_and_or_b32 v4, v4, s0, v1
	v_bitop3_b32 v2, s3, v2, v3 bitop3:0xf6
	v_bitop3_b32 v182, s4, v4, v3 bitop3:0xf6
	v_add_u32_e32 v3, -1, v144
	v_add_u32_e32 v4, 1, v144
	v_and_or_b32 v3, v3, 15, v1
	v_and_or_b32 v1, v4, 15, v1
	v_add_u32_e32 v4, -14, v145
	s_cmpk_lt_u32 s2, 0x100
	v_cmp_gt_u32_e64 s[0:1], -12, v4
	v_add_u32_e32 v4, -12, v145
	v_cmp_gt_u32_e64 s[2:3], 2, v145
	v_mov_b32_e32 v5, 0x5600
	v_cmp_eq_u32_e64 s[10:11], 0, v145
	v_cndmask_b32_e64 v4, v4, v145, s[2:3]
	v_mul_i32_i24_e32 v156, 0x1580, v4
	v_mov_b32_e32 v4, 0x6b80
	v_lshl_or_b32 v186, v0, 3, s12
	v_lshlrev_b32_e32 v0, 9, v144
	v_cndmask_b32_e64 v158, v4, v5, s[10:11]
	v_and_b32_e32 v0, 0x70000, v0
	v_lshlrev_b32_e32 v4, 12, v10
	v_readlane_b32 s36, v246, 0
	v_or3_b32 v0, v8, v0, v4
	v_readlane_b32 s37, v246, 1
	v_add_u32_e32 v160, v0, v9
	v_mov_b32_e32 v160, v240
	v_lshlrev_b32_e32 v0, 5, v11
	s_cselect_b64 s[30:31], -1, 0
	s_ashr_i32 s70, s36, 31
	v_readlane_b32 s36, v246, 25
	v_and_b32_e32 v0, 0xf0000, v0
	s_ashr_i32 s69, s34, 31
	v_readlane_b32 s38, v246, 27
	v_readlane_b32 s48, v246, 37
	v_or3_b32 v0, v8, v0, v4
	v_readlane_b32 s39, v246, 28
	v_readlane_b32 s49, v246, 38
	s_add_u32 s38, s48, 0x5600
	v_add_u32_e32 v162, v0, v9
	v_mov_b32_e32 v162, v241
	v_mbcnt_lo_u32_b32 v0, -1, 0
	v_readlane_b32 s40, v246, 29
	s_addc_u32 s39, s49, 0
	v_mbcnt_hi_u32_b32 v0, -1, v0
	s_waitcnt vmcnt(6)
	v_readlane_b32 s41, v246, 30
	s_add_u32 s40, s48, 0xac00
	v_and_b32_e32 v0, 64, v0
	v_readlane_b32 s42, v246, 31
	v_readlane_b32 s43, v246, 32
	v_readlane_b32 s44, v246, 33
	v_readlane_b32 s45, v246, 34
	s_addc_u32 s41, s49, 0
	s_add_i32 s72, 0, 0x10000
	s_add_i32 s73, 0, 0x14000
	v_add_u32_e32 v189, 0, v2
	v_or_b32_e32 v2, v3, v0
	v_or_b32_e32 v0, v1, v0
	v_ashrrev_i32_e32 v157, 31, v156
	v_cmp_eq_u32_e64 s[4:5], 15, v145
	v_cmp_ne_u32_e64 s[6:7], 15, v145
	v_cmp_ne_u32_e64 s[8:9], 0, v145
	v_or_b32_e32 v183, 16, v145
	v_or_b32_e32 v184, 32, v145
	v_or_b32_e32 v185, 48, v145
	v_readlane_b32 s46, v246, 35
	v_mov_b32_e32 v161, v155
	v_mov_b32_e32 v163, v155
	v_mov_b64_e32 v[164:165], 0x1580
	v_mov_b64_e32 v[166:167], 0x157f
	s_movk_i32 s71, 0x2b1
	v_add_u32_e32 v187, s72, v182
	v_add_u32_e32 v188, s73, v182
	v_and_b32_e32 v230, 15, v144
	v_bfe_u32 v231, v144, 4, 2
	v_and_b32_e32 v232, 7, v230
	v_xor_b32_e32 v231, v231, v232
	v_lshlrev_b32_e32 v231, 4, v231
	v_lshl_or_b32 v231, v230, 7, v231
	v_lshrrev_b32_e32 v232, 8, v144
	v_lshl_or_b32 v189, v232, 13, v231
	v_xor_b32_e32 v242, 64, v189
	v_bfe_u32 v232, v144, 6, 2
	v_lshl_or_b32 v187, v232, 12, v231
	v_add_u32_e32 v187, 0x10000, v187
	v_xor_b32_e32 v188, 64, v187
	v_lshlrev_b32_e32 v190, 2, v2
	v_lshlrev_b32_e32 v191, 2, v0
	s_mov_b32 s74, 0x3e6d3388
	v_mov_b32_e32 v192, 0xbf3a00e3
	s_movk_i32 s75, 0x2b00
	s_mov_b64 s[42:43], 0x5610
	s_mov_b64 s[44:45], 0xac10
	s_barrier
	v_readlane_b32 s37, v246, 26
	v_readlane_b32 s47, v246, 36
	v_readlane_b32 s50, v246, 39
	v_readlane_b32 s51, v246, 40
	s_branch .LBB0_879

; #define PG8_STAGE(bufoff, gbase, voff) do { _Pragma("unroll") for (int _i = 0; _i < 2; ++_i) \
;         __builtin_amdgcn_global_load_lds((const unsigned*)((const char*)(gbase) + (voff)[_i]), (PG8_LAS unsigned*)(lds + (bufoff) + ldsw + _i * 8192), 16, 0, 0); } while (0)
; #define PG8_LDA(dst, b, h) do { _Pragma("unroll") for (int m = 0; m < 4; ++m) _Pragma("unroll") for (int k = 0; k < 2; ++k) dst[m][k] = *(const PG8_LAS bf16x8*)(lds + PG8_SA(b, h) + aoff + m * 2048 + k * 1024); } while (0)
; #define PG8_LDB(dst, b, h) do { _Pragma("unroll") for (int n = 0; n < 2; ++n) _Pragma("unroll") for (int k = 0; k < 2; ++k) dst[n][k] = *(const PG8_LAS bf16x8*)(lds + PG8_SB(b, h) + boff + n * 2048 + k * 1024); } while (0)
; #define PG8_MMA(ai, bj, At, Bt) do { __builtin_amdgcn_s_setprio(1); _Pragma("unroll") for (int m = 0; m < 4; ++m) _Pragma("unroll") for (int n = 0; n < 2; ++n) _Pragma("unroll") for (int k = 0; k < 2; ++k) \
;         acc[ai][bj][m][n] = __builtin_amdgcn_mfma_f32_16x16x32_bf16(Bt[n][k], At[m][k], acc[ai][bj][m][n], 0, 0, 0); __builtin_amdgcn_s_setprio(0); } while (0)
; #define PG8_WAIT_V(n) asm volatile("s_waitcnt vmcnt(" #n ")" ::: "memory")
; #define PG8_WAIT_L(n) asm volatile("s_waitcnt lgkmcnt(" #n ")" ::: "memory")
; #define PG8_BAR __builtin_amdgcn_s_barrier()
; #define PG8_SCHED __builtin_amdgcn_sched_barrier(0)
; template <class Epi, class Sched, bool ALIGN_EPI = false, bool SP2 = false>
; __device__ __forceinline__ void gemm_phase(PG8_LAS unsigned char* lds, const Gemm g, const Sched& S, const Epi& E) {
;     ...
;             PG8_LDB(B0, 0, 0); PG8_LDB(B1, 0, 1); PG8_SCHED; PG8_LDA(At, 0, 0); PG8_STAGE(PG8_SA(1, 1), a1 + hstep, voffA);
;             PG8_WAIT_V(8); PG8_WAIT_L(0); PG8_BAR; PG8_MMA(0, 0, At, B0); PG8_MMA(0, 1, At, B1); PG8_BAR; PG8_SCHED;
;             PG8_LDA(At, 0, 1); PG8_STAGE(PG8_SB(0, 0), b2, voffB); PG8_STAGE(PG8_SB(0, 1), b2 + hstep, voffB); PG8_STAGE(PG8_SA(0, 0), a2, voffA);
;             PG8_WAIT_V(8); PG8_WAIT_L(0); PG8_BAR; PG8_MMA(1, 0, At, B0); PG8_MMA(1, 1, At, B1); PG8_BAR; PG8_SCHED;
.LBB0_882:
	ds_read_b128 v[128:131], v187
	ds_read_b128 v[132:135], v188
	ds_read_b128 v[136:139], v187 offset:2048
	ds_read_b128 v[140:143], v188 offset:2048
	ds_read_b128 v[168:171], v187 offset:16384
	ds_read_b128 v[172:175], v188 offset:16384
	ds_read_b128 v[176:179], v187 offset:18432
	ds_read_b128 v[194:197], v188 offset:18432
	s_add_u32 s20, s18, 0xfff80080
	s_addc_u32 s21, s19, -1
	s_cmp_eq_u32 s78, 28
	s_cselect_b32 s55, s15, s21
	s_cselect_b32 s54, s17, s20
	s_cselect_b32 s21, s47, s77
	s_cselect_b32 s20, s49, s76
	v_lshl_add_u64 v[180:181], s[18:19], 0, v[160:161]
	s_add_i32 m0, s60, 0xc000
	ds_read_b128 v[198:201], v189
	ds_read_b128 v[202:205], v242
	ds_read_b128 v[206:209], v189 offset:2048
	ds_read_b128 v[210:213], v242 offset:2048
	ds_read_b128 v[214:217], v189 offset:4096
	ds_read_b128 v[218:221], v242 offset:4096
	ds_read_b128 v[222:225], v189 offset:6144
	ds_read_b128 v[226:229], v242 offset:6144
	global_load_lds_dwordx4 v[180:181], off
	v_lshl_add_u64 v[180:181], s[18:19], 0, v[162:163]
	s_add_i32 m0, s60, 0xe000
	s_nop 0
	global_load_lds_dwordx4 v[180:181], off
	s_waitcnt vmcnt(8)
	s_waitcnt lgkmcnt(0)
	s_barrier
	s_setprio 1
	s_waitcnt lgkmcnt(0)
	v_mfma_f32_16x16x32_bf16 v[120:123], v[128:131], v[198:201], v[120:123]
	v_mfma_f32_16x16x32_bf16 v[88:91], v[136:139], v[198:201], v[88:91]
	v_mfma_f32_16x16x32_bf16 v[116:119], v[128:131], v[206:209], v[116:119]
	v_mfma_f32_16x16x32_bf16 v[84:87], v[136:139], v[206:209], v[84:87]
	v_mfma_f32_16x16x32_bf16 v[112:115], v[128:131], v[214:217], v[112:115]
	v_mfma_f32_16x16x32_bf16 v[80:83], v[136:139], v[214:217], v[80:83]
	v_mfma_f32_16x16x32_bf16 v[100:103], v[128:131], v[222:225], v[100:103]
	v_mfma_f32_16x16x32_bf16 v[68:71], v[136:139], v[222:225], v[68:71]
	v_mfma_f32_16x16x32_bf16 v[120:123], v[132:135], v[202:205], v[120:123]
	v_mfma_f32_16x16x32_bf16 v[88:91], v[140:143], v[202:205], v[88:91]
	v_mfma_f32_16x16x32_bf16 v[116:119], v[132:135], v[210:213], v[116:119]
	v_mfma_f32_16x16x32_bf16 v[84:87], v[140:143], v[210:213], v[84:87]
	v_mfma_f32_16x16x32_bf16 v[112:115], v[132:135], v[218:221], v[112:115]
	v_mfma_f32_16x16x32_bf16 v[80:83], v[140:143], v[218:221], v[80:83]
	v_mfma_f32_16x16x32_bf16 v[100:103], v[132:135], v[226:229], v[100:103]
	v_mfma_f32_16x16x32_bf16 v[68:71], v[140:143], v[226:229], v[68:71]
	s_setprio 0
	s_setprio 1
	v_mfma_f32_16x16x32_bf16 v[124:127], v[168:171], v[198:201], v[124:127]
	v_mfma_f32_16x16x32_bf16 v[92:95], v[176:179], v[198:201], v[92:95]
	v_mfma_f32_16x16x32_bf16 v[108:111], v[168:171], v[206:209], v[108:111]
	v_mfma_f32_16x16x32_bf16 v[76:79], v[176:179], v[206:209], v[76:79]
	v_mfma_f32_16x16x32_bf16 v[104:107], v[168:171], v[214:217], v[104:107]
	v_mfma_f32_16x16x32_bf16 v[72:75], v[176:179], v[214:217], v[72:75]
	v_mfma_f32_16x16x32_bf16 v[96:99], v[168:171], v[222:225], v[96:99]
	v_mfma_f32_16x16x32_bf16 v[64:67], v[176:179], v[222:225], v[64:67]
	v_mfma_f32_16x16x32_bf16 v[124:127], v[172:175], v[202:205], v[124:127]
	v_mfma_f32_16x16x32_bf16 v[92:95], v[194:197], v[202:205], v[92:95]
	v_mfma_f32_16x16x32_bf16 v[108:111], v[172:175], v[210:213], v[108:111]
	v_mfma_f32_16x16x32_bf16 v[76:79], v[194:197], v[210:213], v[76:79]
	v_mfma_f32_16x16x32_bf16 v[104:107], v[172:175], v[218:221], v[104:107]
	v_mfma_f32_16x16x32_bf16 v[72:75], v[194:197], v[218:221], v[72:75]
	v_mfma_f32_16x16x32_bf16 v[96:99], v[172:175], v[226:229], v[96:99]
	v_mfma_f32_16x16x32_bf16 v[64:67], v[194:197], v[226:229], v[64:67]
	s_setprio 0
	s_barrier
	s_add_i32 s36, s72, s59
	v_lshl_add_u64 v[180:181], s[20:21], 0, v[148:149]
	s_mov_b32 m0, s36
	ds_read_b128 v[198:201], v189 offset:16384
	ds_read_b128 v[202:205], v242 offset:16384
	ds_read_b128 v[206:209], v189 offset:18432
	ds_read_b128 v[210:213], v242 offset:18432
	ds_read_b128 v[214:217], v189 offset:20480
	ds_read_b128 v[218:221], v242 offset:20480
	ds_read_b128 v[222:225], v189 offset:22528
	ds_read_b128 v[226:229], v242 offset:22528
	global_load_lds_dwordx4 v[180:181], off
	s_add_i32 m0, s36, 0x2000
	s_add_u32 s36, s20, 0x80000
	v_lshl_add_u64 v[230:231], s[20:21], 0, v[152:153]
	s_addc_u32 s37, s21, 0
	s_add_i32 s79, s73, s59
	global_load_lds_dwordx4 v[230:231], off
	v_lshl_add_u64 v[232:233], s[36:37], 0, v[148:149]
	s_mov_b32 m0, s79
	v_lshl_add_u64 v[234:235], s[54:55], 0, v[150:151]
	global_load_lds_dwordx4 v[232:233], off
	v_lshl_add_u64 v[232:233], s[36:37], 0, v[152:153]
	s_add_i32 m0, s79, 0x2000
	s_nop 0
	global_load_lds_dwordx4 v[232:233], off
	v_lshl_add_u64 v[232:233], s[54:55], 0, v[146:147]
	s_mov_b32 m0, s60
	s_nop 0
	global_load_lds_dwordx4 v[232:233], off
	s_mov_b32 m0, s61
	s_nop 0
	global_load_lds_dwordx4 v[234:235], off
	s_waitcnt vmcnt(8)
	s_waitcnt lgkmcnt(0)
	s_barrier
; #define PG8_STAGE(bufoff, gbase, voff) do { _Pragma("unroll") for (int _i = 0; _i < 2; ++_i) \
;         __builtin_amdgcn_global_load_lds((const unsigned*)((const char*)(gbase) + (voff)[_i]), (PG8_LAS unsigned*)(lds + (bufoff) + ldsw + _i * 8192), 16, 0, 0); } while (0)
; #define PG8_LDA(dst, b, h) do { _Pragma("unroll") for (int m = 0; m < 4; ++m) _Pragma("unroll") for (int k = 0; k < 2; ++k) dst[m][k] = *(const PG8_LAS bf16x8*)(lds + PG8_SA(b, h) + aoff + m * 2048 + k * 1024); } while (0)
; #define PG8_LDB(dst, b, h) do { _Pragma("unroll") for (int n = 0; n < 2; ++n) _Pragma("unroll") for (int k = 0; k < 2; ++k) dst[n][k] = *(const PG8_LAS bf16x8*)(lds + PG8_SB(b, h) + boff + n * 2048 + k * 1024); } while (0)
; #define PG8_MMA(ai, bj, At, Bt) do { __builtin_amdgcn_s_setprio(1); _Pragma("unroll") for (int m = 0; m < 4; ++m) _Pragma("unroll") for (int n = 0; n < 2; ++n) _Pragma("unroll") for (int k = 0; k < 2; ++k) \
;         acc[ai][bj][m][n] = __builtin_amdgcn_mfma_f32_16x16x32_bf16(Bt[n][k], At[m][k], acc[ai][bj][m][n], 0, 0, 0); __builtin_amdgcn_s_setprio(0); } while (0)
; #define PG8_WAIT_V(n) asm volatile("s_waitcnt vmcnt(" #n ")" ::: "memory")
; #define PG8_WAIT_L(n) asm volatile("s_waitcnt lgkmcnt(" #n ")" ::: "memory")
; #define PG8_BAR __builtin_amdgcn_s_barrier()
; #define PG8_SCHED __builtin_amdgcn_sched_barrier(0)
; template <class Epi, class Sched, bool ALIGN_EPI = false, bool SP2 = false>
; __device__ __forceinline__ void gemm_phase(PG8_LAS unsigned char* lds, const Gemm g, const Sched& S, const Epi& E) {
;     ...
;             PG8_WAIT_V(8); PG8_WAIT_L(0); PG8_BAR; PG8_MMA(1, 0, At, B0); PG8_MMA(1, 1, At, B1); PG8_BAR; PG8_SCHED;
;             PG8_LDB(B0, 1, 0); PG8_LDB(B1, 1, 1); PG8_SCHED; PG8_LDA(At, 1, 0); PG8_STAGE(PG8_SA(0, 1), a2 + hstep, voffA);
;             PG8_WAIT_V(8); PG8_WAIT_L(0); PG8_BAR; PG8_MMA(0, 0, At, B0); PG8_MMA(0, 1, At, B1); PG8_BAR; PG8_SCHED;
	s_setprio 1
	s_waitcnt lgkmcnt(0)
	v_mfma_f32_16x16x32_bf16 v[60:63], v[128:131], v[198:201], v[60:63]
	v_mfma_f32_16x16x32_bf16 v[28:31], v[136:139], v[198:201], v[28:31]
	v_mfma_f32_16x16x32_bf16 v[52:55], v[128:131], v[206:209], v[52:55]
	v_mfma_f32_16x16x32_bf16 v[20:23], v[136:139], v[206:209], v[20:23]
	v_mfma_f32_16x16x32_bf16 v[48:51], v[128:131], v[214:217], v[48:51]
	v_mfma_f32_16x16x32_bf16 v[16:19], v[136:139], v[214:217], v[16:19]
	v_mfma_f32_16x16x32_bf16 v[44:47], v[128:131], v[222:225], v[44:47]
	v_mfma_f32_16x16x32_bf16 v[8:11], v[136:139], v[222:225], v[8:11]
	v_mfma_f32_16x16x32_bf16 v[60:63], v[132:135], v[202:205], v[60:63]
	v_mfma_f32_16x16x32_bf16 v[28:31], v[140:143], v[202:205], v[28:31]
	v_mfma_f32_16x16x32_bf16 v[52:55], v[132:135], v[210:213], v[52:55]
	v_mfma_f32_16x16x32_bf16 v[20:23], v[140:143], v[210:213], v[20:23]
	v_mfma_f32_16x16x32_bf16 v[48:51], v[132:135], v[218:221], v[48:51]
	v_mfma_f32_16x16x32_bf16 v[16:19], v[140:143], v[218:221], v[16:19]
	v_mfma_f32_16x16x32_bf16 v[44:47], v[132:135], v[226:229], v[44:47]
	v_mfma_f32_16x16x32_bf16 v[8:11], v[140:143], v[226:229], v[8:11]
	s_setprio 0
	s_setprio 1
	v_mfma_f32_16x16x32_bf16 v[56:59], v[168:171], v[198:201], v[56:59]
	v_mfma_f32_16x16x32_bf16 v[24:27], v[176:179], v[198:201], v[24:27]
	v_mfma_f32_16x16x32_bf16 v[40:43], v[168:171], v[206:209], v[40:43]
	v_mfma_f32_16x16x32_bf16 v[12:15], v[176:179], v[206:209], v[12:15]
	v_mfma_f32_16x16x32_bf16 v[36:39], v[168:171], v[214:217], v[36:39]
	v_mfma_f32_16x16x32_bf16 v[4:7], v[176:179], v[214:217], v[4:7]
	v_mfma_f32_16x16x32_bf16 v[32:35], v[168:171], v[222:225], v[32:35]
	v_mfma_f32_16x16x32_bf16 v[0:3], v[176:179], v[222:225], v[0:3]
	v_mfma_f32_16x16x32_bf16 v[56:59], v[172:175], v[202:205], v[56:59]
	v_mfma_f32_16x16x32_bf16 v[24:27], v[194:197], v[202:205], v[24:27]
	v_mfma_f32_16x16x32_bf16 v[40:43], v[172:175], v[210:213], v[40:43]
	v_mfma_f32_16x16x32_bf16 v[12:15], v[194:197], v[210:213], v[12:15]
	v_mfma_f32_16x16x32_bf16 v[36:39], v[172:175], v[218:221], v[36:39]
	v_mfma_f32_16x16x32_bf16 v[4:7], v[194:197], v[218:221], v[4:7]
	v_mfma_f32_16x16x32_bf16 v[32:35], v[172:175], v[226:229], v[32:35]
	v_mfma_f32_16x16x32_bf16 v[0:3], v[194:197], v[226:229], v[0:3]
	s_setprio 0
	s_barrier
	s_add_i32 s79, 0, 0x18000
	s_add_i32 s80, 0, 0x1c000
	v_add_u32_e32 v140, s79, v182
	v_add_u32_e32 v154, s80, v182
	ds_read_b128 v[128:131], v187 offset:32768
	ds_read_b128 v[132:135], v188 offset:32768
	ds_read_b128 v[136:139], v187 offset:34816
	ds_read_b128 v[140:143], v188 offset:34816
	ds_read_b128 v[168:171], v187 offset:49152
	ds_read_b128 v[172:175], v188 offset:49152
	ds_read_b128 v[176:179], v187 offset:51200
	ds_read_b128 v[194:197], v188 offset:51200
	s_add_u32 s36, s54, 0x80000
	s_addc_u32 s37, s55, 0
	s_mov_b32 m0, s62
	v_lshl_add_u64 v[236:237], s[36:37], 0, v[146:147]
	ds_read_b128 v[198:201], v189 offset:32768
	ds_read_b128 v[202:205], v242 offset:32768
	ds_read_b128 v[206:209], v189 offset:34816
	ds_read_b128 v[210:213], v242 offset:34816
	ds_read_b128 v[214:217], v189 offset:36864
	ds_read_b128 v[218:221], v242 offset:36864
	ds_read_b128 v[222:225], v189 offset:38912
	ds_read_b128 v[226:229], v242 offset:38912
	global_load_lds_dwordx4 v[236:237], off
	v_lshl_add_u64 v[236:237], s[36:37], 0, v[150:151]
	s_mov_b32 m0, s63
	s_nop 0
	global_load_lds_dwordx4 v[236:237], off
	s_waitcnt vmcnt(8)
	s_waitcnt lgkmcnt(0)
	s_barrier
	s_setprio 1
	s_waitcnt lgkmcnt(0)
	v_mfma_f32_16x16x32_bf16 v[120:123], v[128:131], v[198:201], v[120:123]
	v_mfma_f32_16x16x32_bf16 v[88:91], v[136:139], v[198:201], v[88:91]
	v_mfma_f32_16x16x32_bf16 v[116:119], v[128:131], v[206:209], v[116:119]
	v_mfma_f32_16x16x32_bf16 v[84:87], v[136:139], v[206:209], v[84:87]
	v_mfma_f32_16x16x32_bf16 v[112:115], v[128:131], v[214:217], v[112:115]
	v_mfma_f32_16x16x32_bf16 v[80:83], v[136:139], v[214:217], v[80:83]
	v_mfma_f32_16x16x32_bf16 v[100:103], v[128:131], v[222:225], v[100:103]
	v_mfma_f32_16x16x32_bf16 v[68:71], v[136:139], v[222:225], v[68:71]
	v_mfma_f32_16x16x32_bf16 v[120:123], v[132:135], v[202:205], v[120:123]
	v_mfma_f32_16x16x32_bf16 v[88:91], v[140:143], v[202:205], v[88:91]
	v_mfma_f32_16x16x32_bf16 v[116:119], v[132:135], v[210:213], v[116:119]
	v_mfma_f32_16x16x32_bf16 v[84:87], v[140:143], v[210:213], v[84:87]
	v_mfma_f32_16x16x32_bf16 v[112:115], v[132:135], v[218:221], v[112:115]
	v_mfma_f32_16x16x32_bf16 v[80:83], v[140:143], v[218:221], v[80:83]
	v_mfma_f32_16x16x32_bf16 v[100:103], v[132:135], v[226:229], v[100:103]
	v_mfma_f32_16x16x32_bf16 v[68:71], v[140:143], v[226:229], v[68:71]
	s_setprio 0
	s_setprio 1
	v_mfma_f32_16x16x32_bf16 v[124:127], v[168:171], v[198:201], v[124:127]
	v_mfma_f32_16x16x32_bf16 v[92:95], v[176:179], v[198:201], v[92:95]
	v_mfma_f32_16x16x32_bf16 v[108:111], v[168:171], v[206:209], v[108:111]
	v_mfma_f32_16x16x32_bf16 v[76:79], v[176:179], v[206:209], v[76:79]
	v_mfma_f32_16x16x32_bf16 v[104:107], v[168:171], v[214:217], v[104:107]
	v_mfma_f32_16x16x32_bf16 v[72:75], v[176:179], v[214:217], v[72:75]
	v_mfma_f32_16x16x32_bf16 v[96:99], v[168:171], v[222:225], v[96:99]
	v_mfma_f32_16x16x32_bf16 v[64:67], v[176:179], v[222:225], v[64:67]
	v_mfma_f32_16x16x32_bf16 v[124:127], v[172:175], v[202:205], v[124:127]
	v_mfma_f32_16x16x32_bf16 v[92:95], v[194:197], v[202:205], v[92:95]
	v_mfma_f32_16x16x32_bf16 v[108:111], v[172:175], v[210:213], v[108:111]
	v_mfma_f32_16x16x32_bf16 v[76:79], v[194:197], v[210:213], v[76:79]
	v_mfma_f32_16x16x32_bf16 v[104:107], v[172:175], v[218:221], v[104:107]
	v_mfma_f32_16x16x32_bf16 v[72:75], v[194:197], v[218:221], v[72:75]
	v_mfma_f32_16x16x32_bf16 v[96:99], v[172:175], v[226:229], v[96:99]
	v_mfma_f32_16x16x32_bf16 v[64:67], v[194:197], v[226:229], v[64:67]
	s_setprio 0
	s_barrier
; #define PG8_STAGE(bufoff, gbase, voff) do { _Pragma("unroll") for (int _i = 0; _i < 2; ++_i) \
;         __builtin_amdgcn_global_load_lds((const unsigned*)((const char*)(gbase) + (voff)[_i]), (PG8_LAS unsigned*)(lds + (bufoff) + ldsw + _i * 8192), 16, 0, 0); } while (0)
; #define PG8_LDA(dst, b, h) do { _Pragma("unroll") for (int m = 0; m < 4; ++m) _Pragma("unroll") for (int k = 0; k < 2; ++k) dst[m][k] = *(const PG8_LAS bf16x8*)(lds + PG8_SA(b, h) + aoff + m * 2048 + k * 1024); } while (0)
; #define PG8_MMA(ai, bj, At, Bt) do { __builtin_amdgcn_s_setprio(1); _Pragma("unroll") for (int m = 0; m < 4; ++m) _Pragma("unroll") for (int n = 0; n < 2; ++n) _Pragma("unroll") for (int k = 0; k < 2; ++k) \
;         acc[ai][bj][m][n] = __builtin_amdgcn_mfma_f32_16x16x32_bf16(Bt[n][k], At[m][k], acc[ai][bj][m][n], 0, 0, 0); __builtin_amdgcn_s_setprio(0); } while (0)
; #define PG8_WAIT_V(n) asm volatile("s_waitcnt vmcnt(" #n ")" ::: "memory")
; #define PG8_WAIT_L(n) asm volatile("s_waitcnt lgkmcnt(" #n ")" ::: "memory")
; #define PG8_BAR __builtin_amdgcn_s_barrier()
; #define PG8_SCHED __builtin_amdgcn_sched_barrier(0)
; template <class Epi, class Sched, bool ALIGN_EPI = false, bool SP2 = false>
; __device__ __forceinline__ void gemm_phase(PG8_LAS unsigned char* lds, const Gemm g, const Sched& S, const Epi& E) {
;     ...
;         for (int t = 0; t < nt; t += 2) {
;             const bool last = (t == nt - 2);
;     ...
;             PG8_LDA(At, 1, 1); PG8_STAGE(PG8_SB(1, 0), b3, voffB); PG8_STAGE(PG8_SB(1, 1), b3 + hstep, voffB); PG8_STAGE(PG8_SA(1, 0), a3, voffA);
;             PG8_WAIT_V(8); PG8_WAIT_L(0); PG8_BAR; PG8_MMA(1, 0, At, B0); PG8_MMA(1, 1, At, B1); PG8_BAR; PG8_SCHED;
	s_add_i32 s36, s79, s59
	v_lshl_add_u64 v[180:181], v[180:181], 0, s[28:29]
	s_mov_b32 m0, s36
	ds_read_b128 v[198:201], v189 offset:49152
	ds_read_b128 v[202:205], v242 offset:49152
	ds_read_b128 v[206:209], v189 offset:51200
	ds_read_b128 v[210:213], v242 offset:51200
	ds_read_b128 v[214:217], v189 offset:53248
	ds_read_b128 v[218:221], v242 offset:53248
	ds_read_b128 v[222:225], v189 offset:55296
	ds_read_b128 v[226:229], v242 offset:55296
	global_load_lds_dwordx4 v[180:181], off
	s_add_i32 m0, s36, 0x2000
	s_add_u32 s20, s20, 0x80080
	v_lshl_add_u64 v[180:181], v[230:231], 0, s[28:29]
	s_addc_u32 s21, s21, 0
	s_add_i32 s36, s80, s59
	global_load_lds_dwordx4 v[180:181], off
	v_lshl_add_u64 v[180:181], s[20:21], 0, v[148:149]
	s_mov_b32 m0, s36
	s_nop 0
	global_load_lds_dwordx4 v[180:181], off
	v_lshl_add_u64 v[180:181], s[20:21], 0, v[152:153]
	s_add_i32 m0, s36, 0x2000
	s_nop 0
	global_load_lds_dwordx4 v[180:181], off
	v_lshl_add_u64 v[180:181], v[232:233], 0, s[28:29]
	s_mov_b32 m0, s67
	s_nop 0
	global_load_lds_dwordx4 v[180:181], off
	v_lshl_add_u64 v[180:181], v[234:235], 0, s[28:29]
	s_mov_b32 m0, s68
	s_nop 0
	global_load_lds_dwordx4 v[180:181], off
	s_waitcnt vmcnt(8)
	s_waitcnt lgkmcnt(0)
	s_barrier
	s_setprio 1
	s_waitcnt lgkmcnt(0)
	v_mfma_f32_16x16x32_bf16 v[60:63], v[128:131], v[198:201], v[60:63]
	v_mfma_f32_16x16x32_bf16 v[28:31], v[136:139], v[198:201], v[28:31]
	v_mfma_f32_16x16x32_bf16 v[52:55], v[128:131], v[206:209], v[52:55]
	v_mfma_f32_16x16x32_bf16 v[20:23], v[136:139], v[206:209], v[20:23]
	v_mfma_f32_16x16x32_bf16 v[48:51], v[128:131], v[214:217], v[48:51]
	v_mfma_f32_16x16x32_bf16 v[16:19], v[136:139], v[214:217], v[16:19]
	v_mfma_f32_16x16x32_bf16 v[44:47], v[128:131], v[222:225], v[44:47]
	v_mfma_f32_16x16x32_bf16 v[8:11], v[136:139], v[222:225], v[8:11]
	v_mfma_f32_16x16x32_bf16 v[60:63], v[132:135], v[202:205], v[60:63]
	v_mfma_f32_16x16x32_bf16 v[28:31], v[140:143], v[202:205], v[28:31]
	v_mfma_f32_16x16x32_bf16 v[52:55], v[132:135], v[210:213], v[52:55]
	v_mfma_f32_16x16x32_bf16 v[20:23], v[140:143], v[210:213], v[20:23]
	v_mfma_f32_16x16x32_bf16 v[48:51], v[132:135], v[218:221], v[48:51]
	v_mfma_f32_16x16x32_bf16 v[16:19], v[140:143], v[218:221], v[16:19]
	v_mfma_f32_16x16x32_bf16 v[44:47], v[132:135], v[226:229], v[44:47]
	v_mfma_f32_16x16x32_bf16 v[8:11], v[140:143], v[226:229], v[8:11]
	s_setprio 0
	s_setprio 1
	v_mfma_f32_16x16x32_bf16 v[56:59], v[168:171], v[198:201], v[56:59]
	v_mfma_f32_16x16x32_bf16 v[24:27], v[176:179], v[198:201], v[24:27]
	v_mfma_f32_16x16x32_bf16 v[40:43], v[168:171], v[206:209], v[40:43]
	v_mfma_f32_16x16x32_bf16 v[12:15], v[176:179], v[206:209], v[12:15]
	v_mfma_f32_16x16x32_bf16 v[36:39], v[168:171], v[214:217], v[36:39]
	v_mfma_f32_16x16x32_bf16 v[4:7], v[176:179], v[214:217], v[4:7]
	v_mfma_f32_16x16x32_bf16 v[32:35], v[168:171], v[222:225], v[32:35]
	v_mfma_f32_16x16x32_bf16 v[0:3], v[176:179], v[222:225], v[0:3]
	v_mfma_f32_16x16x32_bf16 v[56:59], v[172:175], v[202:205], v[56:59]
	v_mfma_f32_16x16x32_bf16 v[24:27], v[194:197], v[202:205], v[24:27]
	v_mfma_f32_16x16x32_bf16 v[40:43], v[172:175], v[210:213], v[40:43]
	v_mfma_f32_16x16x32_bf16 v[12:15], v[194:197], v[210:213], v[12:15]
	v_mfma_f32_16x16x32_bf16 v[36:39], v[172:175], v[218:221], v[36:39]
	v_mfma_f32_16x16x32_bf16 v[4:7], v[194:197], v[218:221], v[4:7]
	v_mfma_f32_16x16x32_bf16 v[32:35], v[172:175], v[226:229], v[32:35]
	v_mfma_f32_16x16x32_bf16 v[0:3], v[194:197], v[226:229], v[0:3]
	s_setprio 0
	s_barrier
	s_add_i32 s78, s78, 2
	s_add_u32 s18, s18, 0x100
	s_addc_u32 s19, s19, 0
	s_add_u32 s76, s76, 0x100
	s_addc_u32 s77, s77, 0
	s_cmp_gt_u32 s78, 29
	s_cbranch_scc0 .LBB0_882
	s_and_b64 vcc, exec, s[30:31]
	s_cbranch_vccz .LBB0_885
	s_barrier
